# GLA sample state update (P2): input-state loads and output-state stores non-temporal (read once / final output)
# speedup vs baseline: 1.0026x; 1.0026x over previous
; template <int MODE, bool dry = false>
; __device__ __forceinline__ void gla_unit(const Args& a, LAS unsigned char* lds, int idx, int h, int tid, const float (&wu)[16], float bd) {
;     ...
;             const float* S0 = a.in[I_ST] + (size_t)(idx * 4 + h) * 32768; float* S1 = a.out + O_SS + (size_t)(idx * 4 + h) * 32768;
; #pragma unroll
;             for (int mt = 0; mt < 8; ++mt)
; #pragma unroll
;                 for (int n = 0; n < 2; ++n)
; #pragma unroll
;                     for (int i = 0; i < 4; ++i) { const int dk = 16 * mt + 4 * kq + i, dv = 32 * wave + 16 * n + fr; S1[dk * 256 + dv] = dvec[dk] * S0[dk * 256 + dv] + u[mt][n][i]; }
.LBB0_534:
	s_lshl_b32 s8, s10, 17
	s_lshl_b32 s9, s85, 15
	s_or_b32 s26, s8, s9
	s_lshl_b32 s87, s3, 5
	v_readlane_b32 s36, v252, 1
	v_or_b32_e32 v30, s87, v57
	s_lshl_b64 s[10:11], s[26:27], 2
	v_readlane_b32 s44, v252, 9
	v_readlane_b32 s45, v252, 10
	s_add_u32 s8, s44, s10
	s_addc_u32 s9, s45, s11
	v_mad_u64_u32 v[28:29], s[88:89], v30, s73, v[36:37]
	v_add_u32_e32 v31, v36, v63
	s_add_u32 s10, s74, s10
	s_addc_u32 s11, s75, s11
	v_mov_b32_e32 v47, v33
	v_lshrrev_b32_e32 v45, 4, v176
	v_mul_u32_u24_e32 v29, 0x3fc, v57
	v_lshl_add_u32 v29, v30, 2, v29
	v_lshl_add_u32 v29, v45, 4, v29
	v_lshlrev_b32_e32 v54, 2, v57
	v_add_u32_e32 v54, 0x18e00, v54
	s_mov_b64 s[88:89], s[8:9]
	ds_read_b128 v[20:23], v28 offset:53248
	ds_read_b128 v[16:19], v28 offset:55552
	ds_read_b128 v[128:131], v31 offset:34816
	ds_read_b128 v[132:135], v31 offset:37120
	ds_read_b32 v136, v54
	ds_read_b32 v137, v54 offset:64
	ds_read_b32 v138, v54 offset:128
	ds_read_b32 v139, v54 offset:192
	ds_read_b32 v140, v54 offset:256
	ds_read_b32 v141, v54 offset:320
	ds_read_b32 v142, v54 offset:384
	ds_read_b32 v143, v54 offset:448
	global_load_dwordx4 v[208:211], v29, s[88:89] nt
	global_load_dwordx4 v[212:215], v29, s[88:89] offset:64 nt
	s_add_u32 s88, s88, 0x4000
	s_addc_u32 s89, s89, 0
	global_load_dwordx4 v[216:219], v29, s[88:89] nt
	global_load_dwordx4 v[220:223], v29, s[88:89] offset:64 nt
	s_add_u32 s88, s88, 0x4000
	s_addc_u32 s89, s89, 0
	global_load_dwordx4 v[224:227], v29, s[88:89] nt
	global_load_dwordx4 v[228:231], v29, s[88:89] offset:64 nt
	s_add_u32 s88, s88, 0x4000
	s_addc_u32 s89, s89, 0
	global_load_dwordx4 v[232:235], v29, s[88:89] nt
	global_load_dwordx4 v[236:239], v29, s[88:89] offset:64 nt
	s_add_u32 s88, s88, 0x4000
	s_addc_u32 s89, s89, 0
	s_and_b32 s3, s86, 0x3fffffc0
	v_readlane_b32 s37, v252, 2
	v_readlane_b32 s38, v252, 3
	v_readlane_b32 s39, v252, 4
	v_readlane_b32 s40, v252, 5
	v_readlane_b32 s41, v252, 6
	v_readlane_b32 s42, v252, 7
	v_readlane_b32 s43, v252, 8
	v_readlane_b32 s46, v252, 11
	v_readlane_b32 s47, v252, 12
	v_readlane_b32 s48, v252, 13
	v_readlane_b32 s49, v252, 14
	v_readlane_b32 s50, v252, 15
	v_readlane_b32 s51, v252, 16
	s_waitcnt lgkmcnt(0)
	v_mfma_f32_16x16x32_bf16 v[120:123], v[20:23], v[128:131], 0
	v_mfma_f32_16x16x32_bf16 v[124:127], v[16:19], v[128:131], 0
	ds_read_b128 v[128:131], v31 offset:39424
	s_waitcnt vmcnt(6)
	s_nop 5
	v_fma_f32 v120, v136, v208, v120
	v_fma_f32 v121, v136, v209, v121
	v_fma_f32 v122, v136, v210, v122
	v_fma_f32 v123, v136, v211, v123
	v_fma_f32 v124, v136, v212, v124
	v_fma_f32 v125, v136, v213, v125
	v_fma_f32 v126, v136, v214, v126
	v_fma_f32 v127, v136, v215, v127
	global_store_dwordx4 v29, v[120:123], s[10:11] nt
	global_store_dwordx4 v29, v[124:127], s[10:11] offset:64 nt
	s_add_u32 s10, s10, 0x4000
	s_addc_u32 s11, s11, 0
	global_load_dwordx4 v[208:211], v29, s[88:89] nt
	global_load_dwordx4 v[212:215], v29, s[88:89] offset:64 nt
	s_add_u32 s88, s88, 0x4000
	s_addc_u32 s89, s89, 0
	s_waitcnt lgkmcnt(0)
	v_mfma_f32_16x16x32_bf16 v[120:123], v[20:23], v[132:135], 0
	v_mfma_f32_16x16x32_bf16 v[124:127], v[16:19], v[132:135], 0
	ds_read_b128 v[132:135], v31 offset:41728
	s_waitcnt vmcnt(8)
	s_nop 5
	v_fma_f32 v120, v137, v216, v120
	v_fma_f32 v121, v137, v217, v121
	v_fma_f32 v122, v137, v218, v122
	v_fma_f32 v123, v137, v219, v123
	v_fma_f32 v124, v137, v220, v124
	v_fma_f32 v125, v137, v221, v125
	v_fma_f32 v126, v137, v222, v126
	v_fma_f32 v127, v137, v223, v127
	global_store_dwordx4 v29, v[120:123], s[10:11] nt
	global_store_dwordx4 v29, v[124:127], s[10:11] offset:64 nt
	s_add_u32 s10, s10, 0x4000
	s_addc_u32 s11, s11, 0
	global_load_dwordx4 v[216:219], v29, s[88:89] nt
	global_load_dwordx4 v[220:223], v29, s[88:89] offset:64 nt
	s_add_u32 s88, s88, 0x4000
	s_addc_u32 s89, s89, 0
	s_waitcnt lgkmcnt(0)
	v_mfma_f32_16x16x32_bf16 v[120:123], v[20:23], v[128:131], 0
	v_mfma_f32_16x16x32_bf16 v[124:127], v[16:19], v[128:131], 0
	ds_read_b128 v[128:131], v31 offset:44032
	s_waitcnt vmcnt(10)
	s_nop 5
	v_fma_f32 v120, v138, v224, v120
	v_fma_f32 v121, v138, v225, v121
	v_fma_f32 v122, v138, v226, v122
	v_fma_f32 v123, v138, v227, v123
	v_fma_f32 v124, v138, v228, v124
	v_fma_f32 v125, v138, v229, v125
	v_fma_f32 v126, v138, v230, v126
	v_fma_f32 v127, v138, v231, v127
	global_store_dwordx4 v29, v[120:123], s[10:11] nt
	global_store_dwordx4 v29, v[124:127], s[10:11] offset:64 nt
	s_add_u32 s10, s10, 0x4000
	s_addc_u32 s11, s11, 0
	global_load_dwordx4 v[224:227], v29, s[88:89] nt
	global_load_dwordx4 v[228:231], v29, s[88:89] offset:64 nt
	s_add_u32 s88, s88, 0x4000
	s_addc_u32 s89, s89, 0
	s_waitcnt lgkmcnt(0)
	v_mfma_f32_16x16x32_bf16 v[120:123], v[20:23], v[132:135], 0
	v_mfma_f32_16x16x32_bf16 v[124:127], v[16:19], v[132:135], 0
	ds_read_b128 v[132:135], v31 offset:46336
	s_waitcnt vmcnt(12)
	s_nop 5
	v_fma_f32 v120, v139, v232, v120
	v_fma_f32 v121, v139, v233, v121
	v_fma_f32 v122, v139, v234, v122
	v_fma_f32 v123, v139, v235, v123
	v_fma_f32 v124, v139, v236, v124
	v_fma_f32 v125, v139, v237, v125
	v_fma_f32 v126, v139, v238, v126
	v_fma_f32 v127, v139, v239, v127
	global_store_dwordx4 v29, v[120:123], s[10:11] nt
	global_store_dwordx4 v29, v[124:127], s[10:11] offset:64 nt
	s_add_u32 s10, s10, 0x4000
	s_addc_u32 s11, s11, 0
	global_load_dwordx4 v[232:235], v29, s[88:89] nt
	global_load_dwordx4 v[236:239], v29, s[88:89] offset:64 nt
	s_add_u32 s88, s88, 0x4000
	s_addc_u32 s89, s89, 0
	s_waitcnt lgkmcnt(0)
	v_mfma_f32_16x16x32_bf16 v[120:123], v[20:23], v[128:131], 0
	v_mfma_f32_16x16x32_bf16 v[124:127], v[16:19], v[128:131], 0
	ds_read_b128 v[128:131], v31 offset:48640
	s_waitcnt vmcnt(12)
; __device__ __forceinline__ bf16x8 pk8(f32x4 a, f32x4 b) { u32x4 w; w.x = cvt_pk_bf16(a[0], a[1]); w.y = cvt_pk_bf16(a[2], a[3]); w.z = cvt_pk_bf16(b[0], b[1]); w.w = cvt_pk_bf16(b[2], b[3]); return __builtin_bit_cast(bf16x8, w); }
; template <int MODE, bool dry = false>
; __device__ __forceinline__ void gla_unit(const Args& a, LAS unsigned char* lds, int idx, int h, int tid, const float (&wu)[16], float bd) {
;     ...
;             const float* S0 = a.in[I_ST] + (size_t)(idx * 4 + h) * 32768; float* S1 = a.out + O_SS + (size_t)(idx * 4 + h) * 32768;
; #pragma unroll
;             for (int mt = 0; mt < 8; ++mt)
; #pragma unroll
;                 for (int n = 0; n < 2; ++n)
; #pragma unroll
;                     for (int i = 0; i < 4; ++i) { const int dk = 16 * mt + 4 * kq + i, dv = 32 * wave + 16 * n + fr; S1[dk * 256 + dv] = dvec[dk] * S0[dk * 256 + dv] + u[mt][n][i]; }
;     ...
;         for (int ks = 0; ks < 4; ++ks) { bf16x8 av[2];
; #pragma unroll
;             for (int m = 0; m < 2; ++m) { const int dv = 32 * wave + 16 * m + fr;
;                 if (MODE == 1) av[m] = sraw[ks][m];
;                 else { const float* sp = a.in[I_ST] + (size_t)(idx * 4 + h) * 32768 + (size_t)(32 * ks + 8 * kq) * 256 + dv; f32x4 x0, x1;
; #pragma unroll
;                     for (int j = 0; j < 4; ++j) { x0[j] = sp[j * 256]; x1[j] = sp[(j + 4) * 256]; }
;                     av[m] = pk8(x0, x1); } }
	s_nop 5
	v_fma_f32 v120, v140, v208, v120
	v_fma_f32 v121, v140, v209, v121
	v_fma_f32 v122, v140, v210, v122
	v_fma_f32 v123, v140, v211, v123
	v_fma_f32 v124, v140, v212, v124
	v_fma_f32 v125, v140, v213, v125
	v_fma_f32 v126, v140, v214, v126
	v_fma_f32 v127, v140, v215, v127
	global_store_dwordx4 v29, v[120:123], s[10:11] nt
	global_store_dwordx4 v29, v[124:127], s[10:11] offset:64 nt
	s_add_u32 s10, s10, 0x4000
	s_addc_u32 s11, s11, 0
	s_waitcnt lgkmcnt(0)
	v_mfma_f32_16x16x32_bf16 v[120:123], v[20:23], v[132:135], 0
	v_mfma_f32_16x16x32_bf16 v[124:127], v[16:19], v[132:135], 0
	ds_read_b128 v[132:135], v31 offset:50944
	s_waitcnt vmcnt(10)
	s_nop 5
	v_fma_f32 v120, v141, v216, v120
	v_fma_f32 v121, v141, v217, v121
	v_fma_f32 v122, v141, v218, v122
	v_fma_f32 v123, v141, v219, v123
	v_fma_f32 v124, v141, v220, v124
	v_fma_f32 v125, v141, v221, v125
	v_fma_f32 v126, v141, v222, v126
	v_fma_f32 v127, v141, v223, v127
	global_store_dwordx4 v29, v[120:123], s[10:11] nt
	global_store_dwordx4 v29, v[124:127], s[10:11] offset:64 nt
	s_add_u32 s10, s10, 0x4000
	s_addc_u32 s11, s11, 0
	s_waitcnt lgkmcnt(0)
	v_mfma_f32_16x16x32_bf16 v[120:123], v[20:23], v[128:131], 0
	v_mfma_f32_16x16x32_bf16 v[124:127], v[16:19], v[128:131], 0
	s_waitcnt vmcnt(8)
	s_nop 5
	v_fma_f32 v120, v142, v224, v120
	v_fma_f32 v121, v142, v225, v121
	v_fma_f32 v122, v142, v226, v122
	v_fma_f32 v123, v142, v227, v123
	v_fma_f32 v124, v142, v228, v124
	v_fma_f32 v125, v142, v229, v125
	v_fma_f32 v126, v142, v230, v126
	v_fma_f32 v127, v142, v231, v127
	global_store_dwordx4 v29, v[120:123], s[10:11] nt
	global_store_dwordx4 v29, v[124:127], s[10:11] offset:64 nt
	s_add_u32 s10, s10, 0x4000
	s_addc_u32 s11, s11, 0
	s_waitcnt lgkmcnt(0)
	v_mfma_f32_16x16x32_bf16 v[120:123], v[20:23], v[132:135], 0
	v_mfma_f32_16x16x32_bf16 v[124:127], v[16:19], v[132:135], 0
	s_waitcnt vmcnt(6)
	s_nop 5
	v_fma_f32 v120, v143, v232, v120
	v_fma_f32 v121, v143, v233, v121
	v_fma_f32 v122, v143, v234, v122
	v_fma_f32 v123, v143, v235, v123
	v_fma_f32 v124, v143, v236, v124
	v_fma_f32 v125, v143, v237, v125
	v_fma_f32 v126, v143, v238, v126
	v_fma_f32 v127, v143, v239, v127
	global_store_dwordx4 v29, v[120:123], s[10:11] nt
	global_store_dwordx4 v29, v[124:127], s[10:11] offset:64 nt
	s_add_u32 s10, s10, 0x4000
	s_addc_u32 s11, s11, 0
	v_mov_b32_e32 v31, v33
	v_lshl_add_u64 v[22:23], s[8:9], 0, v[46:47]
	v_lshl_add_u64 v[54:55], v[22:23], 0, s[66:67]
	v_mov_b32_e32 v17, v33
	v_lshlrev_b64 v[20:21], 2, v[30:31]
	v_lshl_add_u64 v[24:25], v[22:23], 0, v[20:21]
	v_add_co_u32_e32 v116, vcc, s72, v24
	v_or_b32_e32 v16, 16, v30
	s_nop 0
	v_addc_co_u32_e32 v117, vcc, 0, v25, vcc
	v_lshl_add_u64 v[30:31], v[22:23], 0, s[64:65]
	v_lshl_add_u64 v[118:119], v[30:31], 0, v[20:21]
	v_lshlrev_b64 v[16:17], 2, v[16:17]
	v_add_co_u32_e32 v128, vcc, s72, v118
	v_lshl_add_u64 v[30:31], v[30:31], 0, v[16:17]
	s_nop 0
	v_addc_co_u32_e32 v129, vcc, 0, v119, vcc
	v_lshl_add_u64 v[22:23], v[22:23], 0, s[68:69]
	v_add_co_u32_e32 v130, vcc, s72, v30
	v_lshl_add_u64 v[120:121], v[54:55], 0, v[20:21]
	v_lshl_add_u64 v[54:55], v[54:55], 0, v[16:17]
	v_lshl_add_u64 v[124:125], v[22:23], 0, v[20:21]
	v_lshl_add_u64 v[126:127], v[22:23], 0, v[16:17]
	v_addc_co_u32_e32 v131, vcc, 0, v31, vcc
	v_add_co_u32_e32 v132, vcc, s72, v120
	s_barrier
	global_load_dword v32, v[24:25], off
	global_load_dword v45, v[24:25], off offset:1024
	global_load_dword v47, v[24:25], off offset:2048
	global_load_dword v49, v[24:25], off offset:3072
	global_load_dword v53, v[24:25], off offset:3136
	global_load_dword v115, v[24:25], off offset:2112
	global_load_dword v138, v[24:25], off offset:1088
	global_load_dword v139, v[24:25], off offset:64
	global_load_dword v140, v[116:117], off
	global_load_dword v141, v[116:117], off offset:1024
	global_load_dword v142, v[116:117], off offset:2048
	global_load_dword v143, v[116:117], off offset:3072
	global_load_dword v144, v[116:117], off offset:3136
	global_load_dword v145, v[116:117], off offset:2112
	global_load_dword v146, v[116:117], off offset:1088
	global_load_dword v147, v[116:117], off offset:64
	ds_read_b128 v[16:19], v28 offset:53248
	ds_read_b128 v[20:23], v28 offset:55552
	global_load_dword v148, v[118:119], off
	global_load_dword v149, v[128:129], off
	global_load_dword v150, v[118:119], off offset:1024
	global_load_dword v151, v[128:129], off offset:1024
	global_load_dword v152, v[118:119], off offset:2048
	global_load_dword v153, v[128:129], off offset:2048
	global_load_dword v154, v[128:129], off offset:3072
	global_load_dword v155, v[118:119], off offset:3072
	global_load_dword v156, v[30:31], off
	global_load_dword v157, v[130:131], off
	global_load_dword v158, v[30:31], off offset:1024
	global_load_dword v159, v[130:131], off offset:1024
	global_load_dword v160, v[30:31], off offset:2048
	global_load_dword v161, v[130:131], off offset:2048
	global_load_dword v162, v[130:131], off offset:3072
	global_load_dword v163, v[30:31], off offset:3072
	v_addc_co_u32_e32 v133, vcc, 0, v121, vcc
	v_add_co_u32_e32 v134, vcc, s72, v54
	ds_read_b128 v[24:27], v109
	ds_read_b128 v[28:31], v109 offset:2304
	v_addc_co_u32_e32 v135, vcc, 0, v55, vcc
	global_load_dword v164, v[120:121], off
	global_load_dword v165, v[132:133], off
	global_load_dword v166, v[120:121], off offset:1024
	global_load_dword v167, v[132:133], off offset:1024
	global_load_dword v168, v[120:121], off offset:2048
	global_load_dword v169, v[132:133], off offset:2048
	global_load_dword v170, v[132:133], off offset:3072
	global_load_dword v171, v[120:121], off offset:3072
	global_load_dword v172, v[54:55], off
	global_load_dword v173, v[134:135], off
	global_load_dword v174, v[54:55], off offset:1024
	global_load_dword v175, v[134:135], off offset:1024
	global_load_dword v177, v[54:55], off offset:2048
	global_load_dword v179, v[134:135], off offset:2048
	global_load_dword v180, v[134:135], off offset:3072
	s_nop 0
	global_load_dword v54, v[54:55], off offset:3072
	v_add_co_u32_e32 v136, vcc, s72, v124
	s_waitcnt lgkmcnt(1)
; #define LAS __attribute__((address_space(3)))
; __device__ __forceinline__ bf16x8 pk8(f32x4 a, f32x4 b) { u32x4 w; w.x = cvt_pk_bf16(a[0], a[1]); w.y = cvt_pk_bf16(a[2], a[3]); w.z = cvt_pk_bf16(b[0], b[1]); w.w = cvt_pk_bf16(b[2], b[3]); return __builtin_bit_cast(bf16x8, w); }
; #define MFMA16(a, b, c) __builtin_amdgcn_mfma_f32_16x16x32_bf16((a), (b), (c), 0, 0, 0)
; template <int MODE, bool dry = false>
; __device__ __forceinline__ void gla_unit(const Args& a, LAS unsigned char* lds, int idx, int h, int tid, const float (&wu)[16], float bd) {
;     ...
;         for (int ks = 0; ks < KS_T; ++ks) { bf16x8 av[2];
; #pragma unroll
;             for (int m = 0; m < 2; ++m) av[m] = *(const LAS bf16x8*)(vT + (32 * wave + 16 * m + fr) * TT_P + 32 * ks + 8 * kq);
; #pragma unroll
;             for (int nt = 0; nt < NTL; ++nt) { const bf16x8 bv = *(const LAS bf16x8*)(att + (16 * nt + fr) * TT_P + 32 * ks + 8 * kq);
; #pragma unroll
;                 for (int m = 0; m < 2; ++m) o[m][nt] = MFMA16(av[m], bv, o[m][nt]); } }
; #pragma unroll
;         for (int ks = 0; ks < 4; ++ks) { bf16x8 av[2];
; #pragma unroll
;             for (int m = 0; m < 2; ++m) { const int dv = 32 * wave + 16 * m + fr;
;                 if (MODE == 1) av[m] = sraw[ks][m];
;                 else { const float* sp = a.in[I_ST] + (size_t)(idx * 4 + h) * 32768 + (size_t)(32 * ks + 8 * kq) * 256 + dv; f32x4 x0, x1;
; #pragma unroll
;                     for (int j = 0; j < 4; ++j) { x0[j] = sp[j * 256]; x1[j] = sp[(j + 4) * 256]; }
;                     av[m] = pk8(x0, x1); } }
; #pragma unroll
;             for (int nt = 0; nt < NTL; ++nt) { const bf16x8 bv = *(const LAS bf16x8*)(qe + (16 * nt + fr) * QE_P + 32 * ks + 8 * kq);
; #pragma unroll
;                 for (int m = 0; m < 2; ++m) o[m][nt] = MFMA16(av[m], bv, o[m][nt]); } }
; #pragma unroll
;         for (int nt = 0; nt < NTL; ++nt) { float ss = 0.f;
; #pragma unroll
;             for (int m = 0; m < 2; ++m) ss += (o[m][nt][0] * o[m][nt][0] + o[m][nt][1] * o[m][nt][1]) + (o[m][nt][2] * o[m][nt][2] + o[m][nt][3] * o[m][nt][3]);
;             ss += __shfl_xor(ss, 16); ss += __shfl_xor(ss, 32);
;             if (kq == 0) red[wave * 64 + 16 * nt + fr] = ss; }
	v_mfma_f32_16x16x32_bf16 v[116:119], v[16:19], v[24:27], 0
	v_addc_co_u32_e32 v137, vcc, 0, v125, vcc
	v_add_co_u32_e32 v122, vcc, s72, v126
	global_load_dword v55, v[124:125], off
	global_load_dword v181, v[136:137], off
	global_load_dword v182, v[124:125], off offset:1024
	global_load_dword v183, v[136:137], off offset:1024
	global_load_dword v184, v[124:125], off offset:2048
	global_load_dword v185, v[136:137], off offset:2048
	global_load_dword v186, v[136:137], off offset:3072
	global_load_dword v187, v[124:125], off offset:3072
	v_addc_co_u32_e32 v123, vcc, 0, v127, vcc
	global_load_dword v188, v[126:127], off
	global_load_dword v189, v[126:127], off offset:1024
	global_load_dword v190, v[122:123], off offset:1024
	global_load_dword v191, v[126:127], off offset:2048
	global_load_dword v192, v[122:123], off offset:2048
	global_load_dword v193, v[122:123], off offset:3072
	global_load_dword v194, v[126:127], off offset:3072
	global_load_dword v195, v[122:123], off
	v_mfma_f32_16x16x32_bf16 v[24:27], v[20:23], v[24:27], 0
	ds_read_b128 v[120:123], v110
	ds_read_b128 v[124:127], v110 offset:64
	s_waitcnt vmcnt(62)
	v_cvt_pk_bf16_f32 v128, v32, v45
	s_waitcnt lgkmcnt(2)
	v_mfma_f32_16x16x32_bf16 v[16:19], v[16:19], v[28:31], 0
	s_waitcnt vmcnt(60)
	v_cvt_pk_bf16_f32 v129, v47, v49
	s_waitcnt vmcnt(45)
	v_cvt_pk_bf16_f32 v136, v148, v150
	v_cvt_pk_bf16_f32 v130, v140, v141
	v_mfma_f32_16x16x32_bf16 v[20:23], v[20:23], v[28:31], 0
	v_cvt_pk_bf16_f32 v131, v142, v143
	v_cvt_pk_bf16_f32 v28, v139, v138
	v_cvt_pk_bf16_f32 v29, v115, v53
	v_cvt_pk_bf16_f32 v31, v145, v144
	v_cvt_pk_bf16_f32 v30, v147, v146
	s_waitcnt lgkmcnt(1)
	v_mfma_f32_16x16x32_bf16 v[116:119], v[128:131], v[120:123], v[116:119]
	s_waitcnt vmcnt(40)
	v_cvt_pk_bf16_f32 v137, v152, v155
	v_cvt_pk_bf16_f32 v138, v149, v151
	v_cvt_pk_bf16_f32 v139, v153, v154
	v_mfma_f32_16x16x32_bf16 v[24:27], v[28:31], v[120:123], v[24:27]
	ds_read_b128 v[120:123], v110 offset:4352
	ds_read_b128 v[132:135], v110 offset:4416
	s_waitcnt lgkmcnt(1)
	v_mfma_f32_16x16x32_bf16 v[20:23], v[28:31], v[120:123], v[20:23]
	s_waitcnt vmcnt(37)
	v_cvt_pk_bf16_f32 v28, v156, v158
	s_waitcnt vmcnt(32)
	v_cvt_pk_bf16_f32 v29, v160, v163
	v_cvt_pk_bf16_f32 v30, v157, v159
	v_cvt_pk_bf16_f32 v31, v161, v162
	v_mfma_f32_16x16x32_bf16 v[16:19], v[128:131], v[120:123], v[16:19]
	s_waitcnt vmcnt(29)
	v_cvt_pk_bf16_f32 v128, v164, v166
	s_waitcnt vmcnt(24)
	v_cvt_pk_bf16_f32 v129, v168, v171
	v_cvt_pk_bf16_f32 v130, v165, v167
	v_mfma_f32_16x16x32_bf16 v[116:119], v[136:139], v[124:127], v[116:119]
	v_cvt_pk_bf16_f32 v131, v169, v170
	v_mfma_f32_16x16x32_bf16 v[24:27], v[28:31], v[124:127], v[24:27]
	ds_read_b128 v[120:123], v110 offset:128
	ds_read_b128 v[124:127], v110 offset:192
	s_waitcnt lgkmcnt(2)
	v_mfma_f32_16x16x32_bf16 v[16:19], v[136:139], v[132:135], v[16:19]
	s_waitcnt vmcnt(13)
	v_cvt_pk_bf16_f32 v136, v55, v182
	s_waitcnt vmcnt(8)
	v_cvt_pk_bf16_f32 v137, v184, v187
	v_cvt_pk_bf16_f32 v138, v181, v183
	v_mfma_f32_16x16x32_bf16 v[20:23], v[28:31], v[132:135], v[20:23]
	v_cvt_pk_bf16_f32 v28, v172, v174
	v_cvt_pk_bf16_f32 v29, v177, v54
	v_cvt_pk_bf16_f32 v30, v173, v175
	v_cvt_pk_bf16_f32 v31, v179, v180
	ds_read_b128 v[132:135], v110 offset:4480
	s_waitcnt lgkmcnt(2)
	v_mfma_f32_16x16x32_bf16 v[116:119], v[128:131], v[120:123], v[116:119]
	v_cvt_pk_bf16_f32 v139, v185, v186
	v_mfma_f32_16x16x32_bf16 v[24:27], v[28:31], v[120:123], v[24:27]
	ds_read_b128 v[120:123], v110 offset:4544
	s_waitcnt lgkmcnt(1)
	v_mfma_f32_16x16x32_bf16 v[16:19], v[128:131], v[132:135], v[16:19]
	s_waitcnt vmcnt(6)
	v_cvt_pk_bf16_f32 v128, v188, v189
	s_waitcnt vmcnt(1)
	v_cvt_pk_bf16_f32 v129, v191, v194
	s_waitcnt vmcnt(0)
	v_cvt_pk_bf16_f32 v130, v195, v190
	v_cvt_pk_bf16_f32 v131, v192, v193
	v_mfma_f32_16x16x32_bf16 v[132:135], v[28:31], v[132:135], v[20:23]
	v_mfma_f32_16x16x32_bf16 v[28:31], v[136:139], v[124:127], v[116:119]
	s_nop 1
	v_and_b32_e32 v21, 64, v114
	v_xor_b32_e32 v20, 16, v114
	v_add_u32_e32 v45, 64, v21
	v_mfma_f32_16x16x32_bf16 v[24:27], v[128:131], v[124:127], v[24:27]
	v_cmp_lt_i32_e32 vcc, v20, v45
	s_nop 1
	v_cndmask_b32_e32 v20, v114, v20, vcc
	v_lshlrev_b32_e32 v32, 2, v20
	s_waitcnt lgkmcnt(0)
	v_mfma_f32_16x16x32_bf16 v[20:23], v[136:139], v[120:123], v[16:19]
	s_nop 2
	v_mul_f32_e32 v16, v29, v29
	v_mul_f32_e32 v17, v31, v31
	v_mul_f32_e32 v18, v25, v25
	v_mul_f32_e32 v19, v27, v27
	v_fmac_f32_e32 v16, v28, v28
	v_fmac_f32_e32 v17, v30, v30
	v_fmac_f32_e32 v18, v24, v24
	v_fmac_f32_e32 v19, v26, v26
	v_add_f32_e32 v16, v16, v17
	v_add_f32_e32 v17, v18, v19
	v_add_f32_e32 v16, v16, v17
	ds_bpermute_b32 v17, v32, v16
	v_xor_b32_e32 v18, 32, v114
	v_cmp_lt_i32_e32 vcc, v18, v45
	v_lshl_add_u32 v45, s3, 2, v65
	s_waitcnt lgkmcnt(0)
	v_add_f32_e32 v49, v16, v17
	v_cndmask_b32_e32 v18, v114, v18, vcc
	v_lshlrev_b32_e32 v47, 2, v18
	ds_bpermute_b32 v53, v47, v49
	v_mfma_f32_16x16x32_bf16 v[16:19], v[128:131], v[120:123], v[132:135]
	s_and_saveexec_b64 s[8:9], s[6:7]
	s_cbranch_execz .LBB0_536
	s_waitcnt lgkmcnt(0)
	v_add_f32_e32 v49, v49, v53
	ds_write_b32 v45, v49
